# attnB loop: LDS-DMA issue one MFMA gap later (gaps 7 and 9)
# baseline (speedup 1.0000x reference)
.Lb_loop:
	s_waitcnt lgkmcnt(0)
	v_mfma_f32_32x32x16_bf16 v[32:47], v[192:195], v[224:227], v[32:47]
	v_mfma_f32_32x32x16_bf16 v[48:63], v[196:199], v[224:227], v[48:63]
	ds_read_b128 v[96:99], v146 offset:33280
	ds_read_b128 v[100:103], v147 offset:33280
	ds_read_b128 v[104:107], v148 offset:33280
	ds_read_b128 v[108:111], v149 offset:33280
	v_mfma_f32_32x32x16_bf16 v[16:31], v[200:203], v[224:227], v[16:31]
	v_exp_f32_e32 v240, v80
	v_exp_f32_e32 v241, v81
	v_exp_f32_e32 v242, v82
	v_mfma_f32_32x32x16_bf16 v[0:15], v[204:207], v[224:227], v[0:15]
	v_exp_f32_e32 v243, v83
	v_exp_f32_e32 v244, v84
	v_exp_f32_e32 v245, v85
	s_waitcnt lgkmcnt(0)
	v_mfma_f32_32x32x16_bf16 v[112:127], v[96:99], v[128:131], v[64:79]
	ds_read_b128 v[96:99], v146 offset:37376
	ds_read_b64_tr_b16 v[192:193], v179 offset:18688
	ds_read_b64_tr_b16 v[194:195], v179 offset:19200
	v_add_f32_e32 v145, v240, v241
	v_cvt_pk_bf16_f32 v232, v240, v241
	v_exp_f32_e32 v246, v86
	v_exp_f32_e32 v247, v87
	v_mfma_f32_32x32x16_bf16 v[112:127], v[100:103], v[132:135], v[112:127]
	ds_read_b128 v[100:103], v147 offset:37376
	ds_read_b64_tr_b16 v[196:197], v179 offset:22848
	ds_read_b64_tr_b16 v[198:199], v179 offset:23360
	v_add_f32_e32 v145, v145, v242
	v_add_f32_e32 v145, v145, v243
	v_cvt_pk_bf16_f32 v233, v242, v243
	v_exp_f32_e32 v240, v88
	v_mfma_f32_32x32x16_bf16 v[112:127], v[104:107], v[136:139], v[112:127]
	ds_read_b128 v[104:107], v148 offset:37376
	ds_read_b64_tr_b16 v[200:201], v179 offset:27008
	ds_read_b64_tr_b16 v[202:203], v179 offset:27520
	s_add_i32 s0, s50, 0xffff8000
	s_and_b32 s0, s0, 0x1f8000
	s_lshl_b32 s4, s0, 1
	s_add_i32 m0, s41, 0x18600
	s_nop 0
	buffer_load_dwordx4 v250, s[8:11], s4 offen lds
	s_add_i32 m0, s41, 0x1a600
	s_nop 0
	buffer_load_dwordx4 v250, s[8:11], s4 offen offset:128 lds
	v_exp_f32_e32 v241, v89
	v_add_f32_e32 v145, v145, v244
	v_add_f32_e32 v145, v145, v245
	v_cvt_pk_bf16_f32 v234, v244, v245
	v_exp_f32_e32 v242, v90
	v_mfma_f32_32x32x16_bf16 v[112:127], v[108:111], v[140:143], v[112:127]
	ds_read_b128 v[108:111], v149 offset:37376
	ds_read_b64_tr_b16 v[204:205], v179 offset:31168
	ds_read_b64_tr_b16 v[206:207], v179 offset:31680
	v_exp_f32_e32 v243, v91
	v_add_f32_e32 v145, v145, v246
	v_add_f32_e32 v145, v145, v247
	v_cvt_pk_bf16_f32 v235, v246, v247
	v_mfma_f32_32x32x16_bf16 v[32:47], v[208:211], v[228:231], v[32:47]
	ds_read_b64_tr_b16 v[208:209], v179 offset:19712
	ds_read_b64_tr_b16 v[210:211], v179 offset:20224
	s_add_i32 m0, s43, 0x18600
	s_nop 0
	buffer_load_dwordx4 v251, s[12:15], s4 offen lds
	s_add_i32 m0, s43, 0x1a600
	s_nop 0
	buffer_load_dwordx4 v251, s[12:15], s4 offen offset:128 lds
	v_exp_f32_e32 v244, v92
	v_exp_f32_e32 v245, v93
	v_add_f32_e32 v145, v145, v240
	v_add_f32_e32 v145, v145, v241
	v_mfma_f32_32x32x16_bf16 v[48:63], v[212:215], v[228:231], v[48:63]
	ds_read_b64_tr_b16 v[212:213], v179 offset:23872
	ds_read_b64_tr_b16 v[214:215], v179 offset:24384
	v_cvt_pk_bf16_f32 v236, v240, v241
	v_exp_f32_e32 v246, v94
	v_exp_f32_e32 v247, v95
	v_mfma_f32_32x32x16_bf16 v[16:31], v[216:219], v[228:231], v[16:31]
	ds_read_b64_tr_b16 v[216:217], v179 offset:28032
	ds_read_b64_tr_b16 v[218:219], v179 offset:28544
	v_add_f32_e32 v145, v145, v242
	v_add_f32_e32 v145, v145, v243
	v_cvt_pk_bf16_f32 v237, v242, v243
	v_add_f32_e32 v145, v145, v244
	v_add_f32_e32 v145, v145, v245
	v_cvt_pk_bf16_f32 v238, v244, v245
	v_mfma_f32_32x32x16_bf16 v[0:15], v[220:223], v[228:231], v[0:15]
	ds_read_b64_tr_b16 v[220:221], v179 offset:32192
	ds_read_b64_tr_b16 v[222:223], v179 offset:32704
	v_add_f32_e32 v145, v145, v246
	v_add_f32_e32 v249, v145, v247
	v_cvt_pk_bf16_f32 v239, v246, v247
	v_add_f32_e32 v249, v248, v249
	v_cmp_lt_f32_e32 vcc, s3, v249
	v_add_f32_e32 v191, v191, v249
	s_waitcnt lgkmcnt(8)
	v_mfma_f32_32x32x16_bf16 v[80:95], v[96:99], v[128:131], v[64:79]
	v_exp_f32_e32 v240, v112
	v_exp_f32_e32 v241, v113
	v_mfma_f32_32x32x16_bf16 v[80:95], v[100:103], v[132:135], v[80:95]
	v_exp_f32_e32 v242, v114
	v_exp_f32_e32 v243, v115
	v_exp_f32_e32 v244, v116
	v_mfma_f32_32x32x16_bf16 v[80:95], v[104:107], v[136:139], v[80:95]
	v_exp_f32_e32 v245, v117
	v_add_f32_e32 v145, v240, v241
	v_cvt_pk_bf16_f32 v224, v240, v241
	v_mfma_f32_32x32x16_bf16 v[80:95], v[108:111], v[140:143], v[80:95]
	v_exp_f32_e32 v246, v118
	v_exp_f32_e32 v247, v119
	v_mfma_f32_32x32x16_bf16 v[32:47], v[192:195], v[232:235], v[32:47]
	ds_read_b64_tr_b16 v[192:193], v180 offset:0
	ds_read_b64_tr_b16 v[194:195], v180 offset:512
	v_add_f32_e32 v145, v145, v242
	v_add_f32_e32 v145, v145, v243
	v_cvt_pk_bf16_f32 v225, v242, v243
	v_exp_f32_e32 v240, v120
	v_mfma_f32_32x32x16_bf16 v[48:63], v[196:199], v[232:235], v[48:63]
	ds_read_b64_tr_b16 v[196:197], v180 offset:4160
	ds_read_b64_tr_b16 v[198:199], v180 offset:4672
	v_exp_f32_e32 v241, v121
	v_add_f32_e32 v145, v145, v244
	v_add_f32_e32 v145, v145, v245
	v_cvt_pk_bf16_f32 v226, v244, v245
	v_mfma_f32_32x32x16_bf16 v[16:31], v[200:203], v[232:235], v[16:31]
	ds_read_b64_tr_b16 v[200:201], v180 offset:8320
	ds_read_b64_tr_b16 v[202:203], v180 offset:8832
	v_exp_f32_e32 v242, v122
	v_exp_f32_e32 v243, v123
	v_mfma_f32_32x32x16_bf16 v[0:15], v[204:207], v[232:235], v[0:15]
	ds_read_b64_tr_b16 v[204:205], v180 offset:12480
	ds_read_b64_tr_b16 v[206:207], v180 offset:12992
	v_add_f32_e32 v145, v145, v246
	v_add_f32_e32 v145, v145, v247
	v_cvt_pk_bf16_f32 v227, v246, v247
	v_exp_f32_e32 v244, v124
	s_waitcnt lgkmcnt(8)
	v_mfma_f32_32x32x16_bf16 v[32:47], v[208:211], v[236:239], v[32:47]
	ds_read_b64_tr_b16 v[208:209], v180 offset:1024
	ds_read_b64_tr_b16 v[210:211], v180 offset:1536
	v_exp_f32_e32 v245, v125
	v_add_f32_e32 v145, v145, v240
	v_add_f32_e32 v145, v145, v241
	v_mfma_f32_32x32x16_bf16 v[48:63], v[212:215], v[236:239], v[48:63]
	ds_read_b64_tr_b16 v[212:213], v180 offset:5184
	ds_read_b64_tr_b16 v[214:215], v180 offset:5696
	v_cvt_pk_bf16_f32 v228, v240, v241
	v_exp_f32_e32 v246, v126
	v_exp_f32_e32 v247, v127
	v_mfma_f32_32x32x16_bf16 v[16:31], v[216:219], v[236:239], v[16:31]
	ds_read_b64_tr_b16 v[216:217], v180 offset:9344
	ds_read_b64_tr_b16 v[218:219], v180 offset:9856
	v_add_f32_e32 v145, v145, v242
	v_add_f32_e32 v145, v145, v243
	v_cvt_pk_bf16_f32 v229, v242, v243
	v_add_f32_e32 v145, v145, v244
	v_mfma_f32_32x32x16_bf16 v[0:15], v[220:223], v[236:239], v[0:15]
	ds_read_b64_tr_b16 v[220:221], v180 offset:13504
	ds_read_b64_tr_b16 v[222:223], v180 offset:14016
	v_add_f32_e32 v145, v145, v245
	v_cvt_pk_bf16_f32 v230, v244, v245
	v_add_f32_e32 v145, v145, v246
	v_add_f32_e32 v248, v145, v247
	v_cvt_pk_bf16_f32 v231, v246, v247
	s_cbranch_vccz .Lb_cont0
	s_branch .Lb_rare0
.Lb_cont0:
	s_waitcnt vmcnt(4)
	s_barrier
	s_waitcnt lgkmcnt(0)
	v_mfma_f32_32x32x16_bf16 v[32:47], v[192:195], v[224:227], v[32:47]
	v_mfma_f32_32x32x16_bf16 v[48:63], v[196:199], v[224:227], v[48:63]
	ds_read_b128 v[96:99], v150 offset:0
	ds_read_b128 v[100:103], v151 offset:0
	ds_read_b128 v[104:107], v152 offset:0
	ds_read_b128 v[108:111], v153 offset:0
	v_mfma_f32_32x32x16_bf16 v[16:31], v[200:203], v[224:227], v[16:31]
	v_exp_f32_e32 v240, v80
	v_exp_f32_e32 v241, v81
	v_exp_f32_e32 v242, v82
	v_mfma_f32_32x32x16_bf16 v[0:15], v[204:207], v[224:227], v[0:15]
	v_exp_f32_e32 v243, v83
	v_exp_f32_e32 v244, v84
	v_exp_f32_e32 v245, v85
	s_waitcnt lgkmcnt(0)
	v_mfma_f32_32x32x16_bf16 v[112:127], v[96:99], v[128:131], v[64:79]
	ds_read_b128 v[96:99], v150 offset:4096
	ds_read_b64_tr_b16 v[192:193], v180 offset:2048
	ds_read_b64_tr_b16 v[194:195], v180 offset:2560
	v_add_f32_e32 v145, v240, v241
	v_cvt_pk_bf16_f32 v232, v240, v241
	v_exp_f32_e32 v246, v86
	v_exp_f32_e32 v247, v87
	v_mfma_f32_32x32x16_bf16 v[112:127], v[100:103], v[132:135], v[112:127]
	ds_read_b128 v[100:103], v151 offset:4096
	ds_read_b64_tr_b16 v[196:197], v180 offset:6208
	ds_read_b64_tr_b16 v[198:199], v180 offset:6720
	v_add_f32_e32 v145, v145, v242
	v_add_f32_e32 v145, v145, v243
	v_cvt_pk_bf16_f32 v233, v242, v243
	v_exp_f32_e32 v240, v88
	v_mfma_f32_32x32x16_bf16 v[112:127], v[104:107], v[136:139], v[112:127]
	ds_read_b128 v[104:107], v152 offset:4096
	ds_read_b64_tr_b16 v[200:201], v180 offset:10368
	ds_read_b64_tr_b16 v[202:203], v180 offset:10880
	s_cmp_gt_u32 s6, 59
	s_cbranch_scc1 .Lb_pn0
	s_and_b32 s0, s50, 0x1f8000
	s_lshl_b32 s4, s0, 1
	s_add_i32 m0, s41, 0x0
	s_nop 0
	buffer_load_dwordx4 v250, s[8:11], s4 offen lds
	s_branch .Lb_po0

.Lb_pn1:
	v_exp_f32_e32 v241, v89
	v_add_f32_e32 v145, v145, v244
	v_add_f32_e32 v145, v145, v245
	v_cvt_pk_bf16_f32 v234, v244, v245
	v_exp_f32_e32 v242, v90
	v_mfma_f32_32x32x16_bf16 v[112:127], v[108:111], v[140:143], v[112:127]
	ds_read_b128 v[108:111], v153 offset:4096
	ds_read_b64_tr_b16 v[204:205], v180 offset:14528
	ds_read_b64_tr_b16 v[206:207], v180 offset:15040
	v_exp_f32_e32 v243, v91
	v_add_f32_e32 v145, v145, v246
	v_add_f32_e32 v145, v145, v247
	v_cvt_pk_bf16_f32 v235, v246, v247
	v_mfma_f32_32x32x16_bf16 v[32:47], v[208:211], v[228:231], v[32:47]
	ds_read_b64_tr_b16 v[208:209], v180 offset:3072
	ds_read_b64_tr_b16 v[210:211], v180 offset:3584
	s_cmp_gt_u32 s6, 59
	s_cbranch_scc1 .Lb_pn2
	s_add_i32 m0, s43, 0x0
	s_nop 0
	buffer_load_dwordx4 v251, s[12:15], s4 offen lds

.Lb_pn3:
	v_exp_f32_e32 v244, v92
	v_exp_f32_e32 v245, v93
	v_add_f32_e32 v145, v145, v240
	v_add_f32_e32 v145, v145, v241
	v_mfma_f32_32x32x16_bf16 v[48:63], v[212:215], v[228:231], v[48:63]
	ds_read_b64_tr_b16 v[212:213], v180 offset:7232
	ds_read_b64_tr_b16 v[214:215], v180 offset:7744
	v_cvt_pk_bf16_f32 v236, v240, v241
	v_exp_f32_e32 v246, v94
	v_exp_f32_e32 v247, v95
	v_mfma_f32_32x32x16_bf16 v[16:31], v[216:219], v[228:231], v[16:31]
	ds_read_b64_tr_b16 v[216:217], v180 offset:11392
	ds_read_b64_tr_b16 v[218:219], v180 offset:11904
	v_add_f32_e32 v145, v145, v242
	v_add_f32_e32 v145, v145, v243
	v_cvt_pk_bf16_f32 v237, v242, v243
	v_add_f32_e32 v145, v145, v244
	v_add_f32_e32 v145, v145, v245
	v_cvt_pk_bf16_f32 v238, v244, v245
	v_mfma_f32_32x32x16_bf16 v[0:15], v[220:223], v[228:231], v[0:15]
	ds_read_b64_tr_b16 v[220:221], v180 offset:15552
	ds_read_b64_tr_b16 v[222:223], v180 offset:16064
	v_add_f32_e32 v145, v145, v246
	v_add_f32_e32 v249, v145, v247
	v_cvt_pk_bf16_f32 v239, v246, v247
	v_add_f32_e32 v249, v248, v249
	v_cmp_lt_f32_e32 vcc, s3, v249
	v_add_f32_e32 v191, v191, v249
	s_waitcnt lgkmcnt(8)
	v_mfma_f32_32x32x16_bf16 v[80:95], v[96:99], v[128:131], v[64:79]
	v_exp_f32_e32 v240, v112
	v_exp_f32_e32 v241, v113
	v_mfma_f32_32x32x16_bf16 v[80:95], v[100:103], v[132:135], v[80:95]
	v_exp_f32_e32 v242, v114
	v_exp_f32_e32 v243, v115
	v_exp_f32_e32 v244, v116
	v_mfma_f32_32x32x16_bf16 v[80:95], v[104:107], v[136:139], v[80:95]
	v_exp_f32_e32 v245, v117
	v_add_f32_e32 v145, v240, v241
	v_cvt_pk_bf16_f32 v224, v240, v241
	v_mfma_f32_32x32x16_bf16 v[80:95], v[108:111], v[140:143], v[80:95]
	v_exp_f32_e32 v246, v118
	v_exp_f32_e32 v247, v119
	v_mfma_f32_32x32x16_bf16 v[32:47], v[192:195], v[232:235], v[32:47]
	ds_read_b64_tr_b16 v[192:193], v182 offset:0
	ds_read_b64_tr_b16 v[194:195], v182 offset:512
	v_add_f32_e32 v145, v145, v242
	v_add_f32_e32 v145, v145, v243
	v_cvt_pk_bf16_f32 v225, v242, v243
	v_exp_f32_e32 v240, v120
	v_mfma_f32_32x32x16_bf16 v[48:63], v[196:199], v[232:235], v[48:63]
	ds_read_b64_tr_b16 v[196:197], v182 offset:4160
	ds_read_b64_tr_b16 v[198:199], v182 offset:4672
	v_exp_f32_e32 v241, v121
	v_add_f32_e32 v145, v145, v244
	v_add_f32_e32 v145, v145, v245
	v_cvt_pk_bf16_f32 v226, v244, v245
	v_mfma_f32_32x32x16_bf16 v[16:31], v[200:203], v[232:235], v[16:31]
	ds_read_b64_tr_b16 v[200:201], v182 offset:8320
	ds_read_b64_tr_b16 v[202:203], v182 offset:8832
	v_exp_f32_e32 v242, v122
	v_exp_f32_e32 v243, v123
	v_mfma_f32_32x32x16_bf16 v[0:15], v[204:207], v[232:235], v[0:15]
	ds_read_b64_tr_b16 v[204:205], v182 offset:12480
	ds_read_b64_tr_b16 v[206:207], v182 offset:12992
	v_add_f32_e32 v145, v145, v246
	v_add_f32_e32 v145, v145, v247
	v_cvt_pk_bf16_f32 v227, v246, v247
	v_exp_f32_e32 v244, v124
	s_waitcnt lgkmcnt(8)
	v_mfma_f32_32x32x16_bf16 v[32:47], v[208:211], v[236:239], v[32:47]
	ds_read_b64_tr_b16 v[208:209], v182 offset:1024
	ds_read_b64_tr_b16 v[210:211], v182 offset:1536
	v_exp_f32_e32 v245, v125
	v_add_f32_e32 v145, v145, v240
	v_add_f32_e32 v145, v145, v241
	v_mfma_f32_32x32x16_bf16 v[48:63], v[212:215], v[236:239], v[48:63]
	ds_read_b64_tr_b16 v[212:213], v182 offset:5184
	ds_read_b64_tr_b16 v[214:215], v182 offset:5696
	v_cvt_pk_bf16_f32 v228, v240, v241
	v_exp_f32_e32 v246, v126
	v_exp_f32_e32 v247, v127
	v_mfma_f32_32x32x16_bf16 v[16:31], v[216:219], v[236:239], v[16:31]
	ds_read_b64_tr_b16 v[216:217], v182 offset:9344
	ds_read_b64_tr_b16 v[218:219], v182 offset:9856
	v_add_f32_e32 v145, v145, v242
	v_add_f32_e32 v145, v145, v243
	v_cvt_pk_bf16_f32 v229, v242, v243
	v_add_f32_e32 v145, v145, v244
	v_mfma_f32_32x32x16_bf16 v[0:15], v[220:223], v[236:239], v[0:15]
	ds_read_b64_tr_b16 v[220:221], v182 offset:13504
	ds_read_b64_tr_b16 v[222:223], v182 offset:14016
	v_add_f32_e32 v145, v145, v245
	v_cvt_pk_bf16_f32 v230, v244, v245
	v_add_f32_e32 v145, v145, v246
	v_add_f32_e32 v248, v145, v247
	v_cvt_pk_bf16_f32 v231, v246, v247
	s_cbranch_vccz .Lb_cont1
	s_branch .Lb_rare1
.Lb_cont1:
	s_waitcnt vmcnt(4)
	s_barrier
	s_waitcnt lgkmcnt(0)
	v_mfma_f32_32x32x16_bf16 v[32:47], v[192:195], v[224:227], v[32:47]
	v_mfma_f32_32x32x16_bf16 v[48:63], v[196:199], v[224:227], v[48:63]
	ds_read_b128 v[96:99], v150 offset:33280
	ds_read_b128 v[100:103], v151 offset:33280
	ds_read_b128 v[104:107], v152 offset:33280
	ds_read_b128 v[108:111], v153 offset:33280
	v_mfma_f32_32x32x16_bf16 v[16:31], v[200:203], v[224:227], v[16:31]
	v_exp_f32_e32 v240, v80
	v_exp_f32_e32 v241, v81
	v_exp_f32_e32 v242, v82
	v_mfma_f32_32x32x16_bf16 v[0:15], v[204:207], v[224:227], v[0:15]
	v_exp_f32_e32 v243, v83
	v_exp_f32_e32 v244, v84
	v_exp_f32_e32 v245, v85
	s_waitcnt lgkmcnt(0)
	v_mfma_f32_32x32x16_bf16 v[112:127], v[96:99], v[128:131], v[64:79]
	ds_read_b128 v[96:99], v150 offset:37376
	ds_read_b64_tr_b16 v[192:193], v182 offset:2048
	ds_read_b64_tr_b16 v[194:195], v182 offset:2560
	v_add_f32_e32 v145, v240, v241
	v_cvt_pk_bf16_f32 v232, v240, v241
	v_exp_f32_e32 v246, v86
	v_exp_f32_e32 v247, v87
	v_mfma_f32_32x32x16_bf16 v[112:127], v[100:103], v[132:135], v[112:127]
	ds_read_b128 v[100:103], v151 offset:37376
	ds_read_b64_tr_b16 v[196:197], v182 offset:6208
	ds_read_b64_tr_b16 v[198:199], v182 offset:6720
	v_add_f32_e32 v145, v145, v242
	v_add_f32_e32 v145, v145, v243
	v_cvt_pk_bf16_f32 v233, v242, v243
	v_exp_f32_e32 v240, v88
	v_mfma_f32_32x32x16_bf16 v[112:127], v[104:107], v[136:139], v[112:127]
	ds_read_b128 v[104:107], v152 offset:37376
	ds_read_b64_tr_b16 v[200:201], v182 offset:10368
	ds_read_b64_tr_b16 v[202:203], v182 offset:10880
	s_cmp_gt_u32 s6, 59
	s_cbranch_scc1 .Lb_pn4
	s_add_i32 s0, s50, 0x8000
	s_and_b32 s0, s0, 0x1f8000
	s_lshl_b32 s4, s0, 1
	s_add_i32 m0, s41, 0x8200
	s_nop 0
	buffer_load_dwordx4 v250, s[8:11], s4 offen lds
	s_branch .Lb_po4

.Lb_pn5:
	v_exp_f32_e32 v241, v89
	v_add_f32_e32 v145, v145, v244
	v_add_f32_e32 v145, v145, v245
	v_cvt_pk_bf16_f32 v234, v244, v245
	v_exp_f32_e32 v242, v90
	v_mfma_f32_32x32x16_bf16 v[112:127], v[108:111], v[140:143], v[112:127]
	ds_read_b128 v[108:111], v153 offset:37376
	ds_read_b64_tr_b16 v[204:205], v182 offset:14528
	ds_read_b64_tr_b16 v[206:207], v182 offset:15040
	v_exp_f32_e32 v243, v91
	v_add_f32_e32 v145, v145, v246
	v_add_f32_e32 v145, v145, v247
	v_cvt_pk_bf16_f32 v235, v246, v247
	v_mfma_f32_32x32x16_bf16 v[32:47], v[208:211], v[228:231], v[32:47]
	ds_read_b64_tr_b16 v[208:209], v182 offset:3072
	ds_read_b64_tr_b16 v[210:211], v182 offset:3584
	s_cmp_gt_u32 s6, 59
	s_cbranch_scc1 .Lb_pn6
	s_add_i32 m0, s43, 0x8200
	s_nop 0
	buffer_load_dwordx4 v251, s[12:15], s4 offen lds

.Lb_pn7:
	v_exp_f32_e32 v244, v92
	v_exp_f32_e32 v245, v93
	v_add_f32_e32 v145, v145, v240
	v_add_f32_e32 v145, v145, v241
	v_mfma_f32_32x32x16_bf16 v[48:63], v[212:215], v[228:231], v[48:63]
	ds_read_b64_tr_b16 v[212:213], v182 offset:7232
	ds_read_b64_tr_b16 v[214:215], v182 offset:7744
	v_cvt_pk_bf16_f32 v236, v240, v241
	v_exp_f32_e32 v246, v94
	v_exp_f32_e32 v247, v95
	v_mfma_f32_32x32x16_bf16 v[16:31], v[216:219], v[228:231], v[16:31]
	ds_read_b64_tr_b16 v[216:217], v182 offset:11392
	ds_read_b64_tr_b16 v[218:219], v182 offset:11904
	v_add_f32_e32 v145, v145, v242
	v_add_f32_e32 v145, v145, v243
	v_cvt_pk_bf16_f32 v237, v242, v243
	v_add_f32_e32 v145, v145, v244
	v_add_f32_e32 v145, v145, v245
	v_cvt_pk_bf16_f32 v238, v244, v245
	v_mfma_f32_32x32x16_bf16 v[0:15], v[220:223], v[228:231], v[0:15]
	ds_read_b64_tr_b16 v[220:221], v182 offset:15552
	ds_read_b64_tr_b16 v[222:223], v182 offset:16064
	v_add_f32_e32 v145, v145, v246
	v_add_f32_e32 v249, v145, v247
	v_cvt_pk_bf16_f32 v239, v246, v247
	v_add_f32_e32 v249, v248, v249
	v_cmp_lt_f32_e32 vcc, s3, v249
	v_add_f32_e32 v191, v191, v249
	s_waitcnt lgkmcnt(8)
	v_mfma_f32_32x32x16_bf16 v[80:95], v[96:99], v[128:131], v[64:79]
	v_exp_f32_e32 v240, v112
	v_exp_f32_e32 v241, v113
	v_mfma_f32_32x32x16_bf16 v[80:95], v[100:103], v[132:135], v[80:95]
	v_exp_f32_e32 v242, v114
	v_exp_f32_e32 v243, v115
	v_exp_f32_e32 v244, v116
	v_mfma_f32_32x32x16_bf16 v[80:95], v[104:107], v[136:139], v[80:95]
	v_exp_f32_e32 v245, v117
	v_add_f32_e32 v145, v240, v241
	v_cvt_pk_bf16_f32 v224, v240, v241
	v_mfma_f32_32x32x16_bf16 v[80:95], v[108:111], v[140:143], v[80:95]
	v_exp_f32_e32 v246, v118
	v_exp_f32_e32 v247, v119
	v_mfma_f32_32x32x16_bf16 v[32:47], v[192:195], v[232:235], v[32:47]
	ds_read_b64_tr_b16 v[192:193], v182 offset:33280
	ds_read_b64_tr_b16 v[194:195], v182 offset:33792
	v_add_f32_e32 v145, v145, v242
	v_add_f32_e32 v145, v145, v243
	v_cvt_pk_bf16_f32 v225, v242, v243
	v_exp_f32_e32 v240, v120
	v_mfma_f32_32x32x16_bf16 v[48:63], v[196:199], v[232:235], v[48:63]
	ds_read_b64_tr_b16 v[196:197], v182 offset:37440
	ds_read_b64_tr_b16 v[198:199], v182 offset:37952
	v_exp_f32_e32 v241, v121
	v_add_f32_e32 v145, v145, v244
	v_add_f32_e32 v145, v145, v245
	v_cvt_pk_bf16_f32 v226, v244, v245
	v_mfma_f32_32x32x16_bf16 v[16:31], v[200:203], v[232:235], v[16:31]
	ds_read_b64_tr_b16 v[200:201], v182 offset:41600
	ds_read_b64_tr_b16 v[202:203], v182 offset:42112
	v_exp_f32_e32 v242, v122
	v_exp_f32_e32 v243, v123
	v_mfma_f32_32x32x16_bf16 v[0:15], v[204:207], v[232:235], v[0:15]
	ds_read_b64_tr_b16 v[204:205], v182 offset:45760
	ds_read_b64_tr_b16 v[206:207], v182 offset:46272
	v_add_f32_e32 v145, v145, v246
	v_add_f32_e32 v145, v145, v247
	v_cvt_pk_bf16_f32 v227, v246, v247
	v_exp_f32_e32 v244, v124
	s_waitcnt lgkmcnt(8)
	v_mfma_f32_32x32x16_bf16 v[32:47], v[208:211], v[236:239], v[32:47]
	ds_read_b64_tr_b16 v[208:209], v182 offset:34304
	ds_read_b64_tr_b16 v[210:211], v182 offset:34816
	v_exp_f32_e32 v245, v125
	v_add_f32_e32 v145, v145, v240
	v_add_f32_e32 v145, v145, v241
	v_mfma_f32_32x32x16_bf16 v[48:63], v[212:215], v[236:239], v[48:63]
	ds_read_b64_tr_b16 v[212:213], v182 offset:38464
	ds_read_b64_tr_b16 v[214:215], v182 offset:38976
	v_cvt_pk_bf16_f32 v228, v240, v241
	v_exp_f32_e32 v246, v126
	v_exp_f32_e32 v247, v127
	v_mfma_f32_32x32x16_bf16 v[16:31], v[216:219], v[236:239], v[16:31]
	ds_read_b64_tr_b16 v[216:217], v182 offset:42624
	ds_read_b64_tr_b16 v[218:219], v182 offset:43136
	v_add_f32_e32 v145, v145, v242
	v_add_f32_e32 v145, v145, v243
	v_cvt_pk_bf16_f32 v229, v242, v243
	v_add_f32_e32 v145, v145, v244
	v_mfma_f32_32x32x16_bf16 v[0:15], v[220:223], v[236:239], v[0:15]
	ds_read_b64_tr_b16 v[220:221], v182 offset:46784
	ds_read_b64_tr_b16 v[222:223], v182 offset:47296
	v_add_f32_e32 v145, v145, v245
	v_cvt_pk_bf16_f32 v230, v244, v245
	v_add_f32_e32 v145, v145, v246
	v_add_f32_e32 v248, v145, v247
	v_cvt_pk_bf16_f32 v231, v246, v247
	s_cbranch_vccz .Lb_cont2
	s_branch .Lb_rare2
.Lb_cont2:
	s_waitcnt vmcnt(4)
	s_barrier
	s_cmp_gt_u32 s6, 59
	s_cbranch_scc1 .Lb_final
	s_waitcnt lgkmcnt(0)
	v_mfma_f32_32x32x16_bf16 v[32:47], v[192:195], v[224:227], v[32:47]
	v_mfma_f32_32x32x16_bf16 v[48:63], v[196:199], v[224:227], v[48:63]
	ds_read_b128 v[96:99], v146 offset:0
	ds_read_b128 v[100:103], v147 offset:0
	ds_read_b128 v[104:107], v148 offset:0
	ds_read_b128 v[108:111], v149 offset:0
	v_mfma_f32_32x32x16_bf16 v[16:31], v[200:203], v[224:227], v[16:31]
	v_exp_f32_e32 v240, v80
	v_exp_f32_e32 v241, v81
	v_exp_f32_e32 v242, v82
	v_mfma_f32_32x32x16_bf16 v[0:15], v[204:207], v[224:227], v[0:15]
	v_exp_f32_e32 v243, v83
	v_exp_f32_e32 v244, v84
	v_exp_f32_e32 v245, v85
	s_waitcnt lgkmcnt(0)
	v_mfma_f32_32x32x16_bf16 v[112:127], v[96:99], v[128:131], v[64:79]
	ds_read_b128 v[96:99], v146 offset:4096
	ds_read_b64_tr_b16 v[192:193], v182 offset:35328
	ds_read_b64_tr_b16 v[194:195], v182 offset:35840
	v_add_f32_e32 v145, v240, v241
	v_cvt_pk_bf16_f32 v232, v240, v241
	v_exp_f32_e32 v246, v86
	v_exp_f32_e32 v247, v87
	v_mfma_f32_32x32x16_bf16 v[112:127], v[100:103], v[132:135], v[112:127]
	ds_read_b128 v[100:103], v147 offset:4096
	ds_read_b64_tr_b16 v[196:197], v182 offset:39488
	ds_read_b64_tr_b16 v[198:199], v182 offset:40000
	v_add_f32_e32 v145, v145, v242
	v_add_f32_e32 v145, v145, v243
	v_cvt_pk_bf16_f32 v233, v242, v243
	v_exp_f32_e32 v240, v88
	v_mfma_f32_32x32x16_bf16 v[112:127], v[104:107], v[136:139], v[112:127]
	ds_read_b128 v[104:107], v148 offset:4096
	ds_read_b64_tr_b16 v[200:201], v182 offset:43648
	ds_read_b64_tr_b16 v[202:203], v182 offset:44160
	s_add_i32 s0, s50, 0x10000
	s_and_b32 s0, s0, 0x1f8000
	s_lshl_b32 s4, s0, 1
	s_add_i32 m0, s41, 0x10400
	s_nop 0
	buffer_load_dwordx4 v250, s[8:11], s4 offen lds
	s_add_i32 m0, s41, 0x12400
	s_nop 0
	buffer_load_dwordx4 v250, s[8:11], s4 offen offset:128 lds
	v_exp_f32_e32 v241, v89
	v_add_f32_e32 v145, v145, v244
	v_add_f32_e32 v145, v145, v245
	v_cvt_pk_bf16_f32 v234, v244, v245
	v_exp_f32_e32 v242, v90
	v_mfma_f32_32x32x16_bf16 v[112:127], v[108:111], v[140:143], v[112:127]
	ds_read_b128 v[108:111], v149 offset:4096
	ds_read_b64_tr_b16 v[204:205], v182 offset:47808
	ds_read_b64_tr_b16 v[206:207], v182 offset:48320
	v_exp_f32_e32 v243, v91
	v_add_f32_e32 v145, v145, v246
	v_add_f32_e32 v145, v145, v247
	v_cvt_pk_bf16_f32 v235, v246, v247
	v_mfma_f32_32x32x16_bf16 v[32:47], v[208:211], v[228:231], v[32:47]
	ds_read_b64_tr_b16 v[208:209], v182 offset:36352
	ds_read_b64_tr_b16 v[210:211], v182 offset:36864
	s_add_i32 m0, s43, 0x10400
	s_nop 0
	buffer_load_dwordx4 v251, s[12:15], s4 offen lds
	s_add_i32 m0, s43, 0x12400
	s_nop 0
	buffer_load_dwordx4 v251, s[12:15], s4 offen offset:128 lds
	v_exp_f32_e32 v244, v92
	v_exp_f32_e32 v245, v93
	v_add_f32_e32 v145, v145, v240
	v_add_f32_e32 v145, v145, v241
	v_mfma_f32_32x32x16_bf16 v[48:63], v[212:215], v[228:231], v[48:63]
	ds_read_b64_tr_b16 v[212:213], v182 offset:40512
	ds_read_b64_tr_b16 v[214:215], v182 offset:41024
	v_cvt_pk_bf16_f32 v236, v240, v241
	v_exp_f32_e32 v246, v94
	v_exp_f32_e32 v247, v95
	v_mfma_f32_32x32x16_bf16 v[16:31], v[216:219], v[228:231], v[16:31]
	ds_read_b64_tr_b16 v[216:217], v182 offset:44672
	ds_read_b64_tr_b16 v[218:219], v182 offset:45184
	v_add_f32_e32 v145, v145, v242
	v_add_f32_e32 v145, v145, v243
	v_cvt_pk_bf16_f32 v237, v242, v243
	v_add_f32_e32 v145, v145, v244
	v_add_f32_e32 v145, v145, v245
	v_cvt_pk_bf16_f32 v238, v244, v245
	v_mfma_f32_32x32x16_bf16 v[0:15], v[220:223], v[228:231], v[0:15]
	ds_read_b64_tr_b16 v[220:221], v182 offset:48832
	ds_read_b64_tr_b16 v[222:223], v182 offset:49344
	v_add_f32_e32 v145, v145, v246
	v_add_f32_e32 v249, v145, v247
	v_cvt_pk_bf16_f32 v239, v246, v247
	v_add_f32_e32 v249, v248, v249
	v_cmp_lt_f32_e32 vcc, s3, v249
	v_add_f32_e32 v191, v191, v249
	s_waitcnt lgkmcnt(8)
	v_mfma_f32_32x32x16_bf16 v[80:95], v[96:99], v[128:131], v[64:79]
	v_exp_f32_e32 v240, v112
	v_exp_f32_e32 v241, v113
	v_mfma_f32_32x32x16_bf16 v[80:95], v[100:103], v[132:135], v[80:95]
	v_exp_f32_e32 v242, v114
	v_exp_f32_e32 v243, v115
	v_exp_f32_e32 v244, v116
	v_mfma_f32_32x32x16_bf16 v[80:95], v[104:107], v[136:139], v[80:95]
	v_exp_f32_e32 v245, v117
	v_add_f32_e32 v145, v240, v241
	v_cvt_pk_bf16_f32 v224, v240, v241
	v_mfma_f32_32x32x16_bf16 v[80:95], v[108:111], v[140:143], v[80:95]
	v_exp_f32_e32 v246, v118
	v_exp_f32_e32 v247, v119
	v_mfma_f32_32x32x16_bf16 v[32:47], v[192:195], v[232:235], v[32:47]
	ds_read_b64_tr_b16 v[192:193], v179 offset:16640
	ds_read_b64_tr_b16 v[194:195], v179 offset:17152
	v_add_f32_e32 v145, v145, v242
	v_add_f32_e32 v145, v145, v243
	v_cvt_pk_bf16_f32 v225, v242, v243
	v_exp_f32_e32 v240, v120
	v_mfma_f32_32x32x16_bf16 v[48:63], v[196:199], v[232:235], v[48:63]
	ds_read_b64_tr_b16 v[196:197], v179 offset:20800
	ds_read_b64_tr_b16 v[198:199], v179 offset:21312
	v_exp_f32_e32 v241, v121
	v_add_f32_e32 v145, v145, v244
	v_add_f32_e32 v145, v145, v245
	v_cvt_pk_bf16_f32 v226, v244, v245
	v_mfma_f32_32x32x16_bf16 v[16:31], v[200:203], v[232:235], v[16:31]
	ds_read_b64_tr_b16 v[200:201], v179 offset:24960
	ds_read_b64_tr_b16 v[202:203], v179 offset:25472
	v_exp_f32_e32 v242, v122
	v_exp_f32_e32 v243, v123
	v_mfma_f32_32x32x16_bf16 v[0:15], v[204:207], v[232:235], v[0:15]
	ds_read_b64_tr_b16 v[204:205], v179 offset:29120
	ds_read_b64_tr_b16 v[206:207], v179 offset:29632
	v_add_f32_e32 v145, v145, v246
	v_add_f32_e32 v145, v145, v247
	v_cvt_pk_bf16_f32 v227, v246, v247
	v_exp_f32_e32 v244, v124
	s_waitcnt lgkmcnt(8)
	v_mfma_f32_32x32x16_bf16 v[32:47], v[208:211], v[236:239], v[32:47]
	ds_read_b64_tr_b16 v[208:209], v179 offset:17664
	ds_read_b64_tr_b16 v[210:211], v179 offset:18176
	v_exp_f32_e32 v245, v125
	v_add_f32_e32 v145, v145, v240
	v_add_f32_e32 v145, v145, v241
	v_mfma_f32_32x32x16_bf16 v[48:63], v[212:215], v[236:239], v[48:63]
	ds_read_b64_tr_b16 v[212:213], v179 offset:21824
	ds_read_b64_tr_b16 v[214:215], v179 offset:22336
	v_cvt_pk_bf16_f32 v228, v240, v241
	v_exp_f32_e32 v246, v126
	v_exp_f32_e32 v247, v127
	v_mfma_f32_32x32x16_bf16 v[16:31], v[216:219], v[236:239], v[16:31]
	ds_read_b64_tr_b16 v[216:217], v179 offset:25984
	ds_read_b64_tr_b16 v[218:219], v179 offset:26496
	v_add_f32_e32 v145, v145, v242
	v_add_f32_e32 v145, v145, v243
	v_cvt_pk_bf16_f32 v229, v242, v243
	v_add_f32_e32 v145, v145, v244
	v_mfma_f32_32x32x16_bf16 v[0:15], v[220:223], v[236:239], v[0:15]
	ds_read_b64_tr_b16 v[220:221], v179 offset:30144
	ds_read_b64_tr_b16 v[222:223], v179 offset:30656
	v_add_f32_e32 v145, v145, v245
	v_cvt_pk_bf16_f32 v230, v244, v245
	v_add_f32_e32 v145, v145, v246
	v_add_f32_e32 v248, v145, v247
	v_cvt_pk_bf16_f32 v231, v246, v247
	s_cbranch_vccz .Lb_cont3
	s_branch .Lb_rare3
